# RMW scan pass: old-y tile loaded with coalesced dwordx4 and redistributed through LDS
# baseline (speedup 1.0000x reference)
; #define LAS __attribute__((address_space(3)))
; template <bool XW, int PASS, bool RMW> ...
;     ...
;     {
;       const int c0 = pass == 0 ? 0 : nc - 1, c1 = pass == 0 ? 1 : nc - 2;
;       if constexpr (XW) {
; #pragma unroll
;         for (int s = 0; s < 16; ++s) qf[s] = ldg16(qr, qoff0 + (unsigned)c0 * 262144u + 1024u * s);
;         if constexpr (PASS == 1 && RMW) {
; #pragma unroll
;           for (int gq = 0; gq < 8; ++gq) ovn[gq] = *(const u32x2*)((const char*)y + (yoff0 + (unsigned)c0 * 524288u + 64u * (gq >> 2) + 16u * (gq & 3)));
;         }
;       }
; #pragma unroll
;       for (int s = 0; s < 8; ++s) kb0[s] = ldg16(kT, kboff0 + (unsigned)c0 * 262144u + 1024u * s);
; #pragma unroll
;       for (int t = 0; t < 2; ++t) {
;         const int sv = 2 * dq + t;
;         const bf16x8 raw = ldg16(vT, vaoff0 + (unsigned)c0 * 524288u + 1024u * sv);
;         *(LAS bf16x8*)(vimg + et * 8192 + sv * 1024 + lane * 16) = scale_tab(raw, kdec + 16 * sv + 8 * h);
;         vr[t] = ldg16(vT, vaoff0 + (unsigned)c1 * 524288u + 1024u * sv);
;       }
;       lds_barrier();
.LBB0_101:
	s_or_b64 exec, exec, s[0:1]
	v_add_u32_e32 v0, s21, v224
	v_or_b32_e32 v1, s3, v0
	s_waitcnt lgkmcnt(0)
	s_barrier
	global_load_dwordx4 v[8:11], v1, s[16:17]
	ds_read_b128 v[12:15], v228
	ds_read_b128 v[16:19], v228 offset:16
	v_add_u32_e32 v1, s20, v226
	v_add_u32_e32 v6, s20, v223
	v_add_u32_e32 v7, s21, v227
	v_or_b32_e32 v2, 0x400, v1
	v_or_b32_e32 v3, 0x800, v1
	v_or_b32_e32 v4, 0xc00, v1
	v_or_b32_e32 v5, 0x1000, v1
	v_or_b32_e32 v40, 0x1800, v6
	v_or_b32_e32 v41, 0x1c00, v6
	v_or_b32_e32 v20, 0x1400, v1
	v_or_b32_e32 v21, 0x1800, v1
	v_or_b32_e32 v22, 0x1c00, v1
	v_or_b32_e32 v23, 0x2000, v1
	v_or_b32_e32 v28, 0x2400, v1
	v_or_b32_e32 v29, 0x2800, v1
	v_or_b32_e32 v30, 0x2c00, v1
	v_or_b32_e32 v31, 0x3000, v1
	v_or_b32_e32 v32, 0x3400, v1
	v_or_b32_e32 v33, 0x3800, v1
	v_or_b32_e32 v34, 0x3c00, v1
	s_waitcnt vmcnt(1)
	v_or_b32_e32 v148, 16, v7
	v_or_b32_e32 v146, 32, v7
	v_or_b32_e32 v145, 48, v7
	v_or_b32_e32 v150, 64, v7
	v_or_b32_e32 v149, 0x50, v7
	v_or_b32_e32 v147, 0x60, v7
	v_or_b32_e32 v144, 0x70, v7
	v_or_b32_e32 v35, 0x400, v6
	v_or_b32_e32 v36, 0x800, v6
	v_or_b32_e32 v37, 0xc00, v6
	v_or_b32_e32 v38, 0x1000, v6
	v_or_b32_e32 v39, 0x1400, v6
	global_load_dwordx4 v[24:27], v1, s[92:93]
	global_load_dwordx4 v[100:103], v2, s[92:93]
	global_load_dwordx4 v[104:107], v3, s[92:93]
	global_load_dwordx4 v[108:111], v4, s[92:93]
	global_load_dwordx4 v[112:115], v5, s[92:93]
	global_load_dwordx4 v[116:119], v20, s[92:93]
	global_load_dwordx4 v[120:123], v21, s[92:93]
	global_load_dwordx4 v[124:127], v22, s[92:93]
	global_load_dwordx4 v[152:155], v23, s[92:93]
	global_load_dwordx4 v[156:159], v28, s[92:93]
	global_load_dwordx4 v[80:83], v29, s[92:93]
	global_load_dwordx4 v[76:79], v30, s[92:93]
	global_load_dwordx4 v[2:5], v31, s[92:93]
	global_load_dwordx4 v[72:75], v32, s[92:93]
	global_load_dwordx4 v[68:71], v33, s[92:93]
	global_load_dwordx4 v[64:67], v34, s[92:93]
	global_load_dwordx2 v[98:99], v7, s[18:19]
	global_load_dwordx2 v[94:95], v148, s[18:19]
	global_load_dwordx2 v[88:89], v146, s[18:19]
	global_load_dwordx2 v[84:85], v145, s[18:19]
	global_load_dwordx2 v[96:97], v150, s[18:19]
	global_load_dwordx2 v[92:93], v149, s[18:19]
	global_load_dwordx2 v[90:91], v147, s[18:19]
	global_load_dwordx2 v[86:87], v144, s[18:19]
	global_load_dwordx4 v[132:135], v6, s[14:15]
	global_load_dwordx4 v[140:143], v35, s[14:15]
	global_load_dwordx4 v[136:139], v36, s[14:15]
	global_load_dwordx4 v[128:131], v37, s[14:15]
	global_load_dwordx4 v[60:63], v38, s[14:15]
	global_load_dwordx4 v[56:59], v39, s[14:15]
	global_load_dwordx4 v[44:47], v40, s[14:15]
	s_nop 0
	global_load_dwordx4 v[40:43], v41, s[14:15]
	v_or_b32_e32 v0, s33, v0
	s_mov_b32 s0, 1
	s_movk_i32 s1, 0x4000
	s_waitcnt vmcnt(32)
	v_lshlrev_b32_e32 v1, 16, v8
	v_and_b32_e32 v6, 0xffff0000, v8
	v_lshlrev_b32_e32 v8, 16, v9
	v_and_b32_e32 v9, 0xffff0000, v9
	v_lshlrev_b32_e32 v20, 16, v10
	v_and_b32_e32 v10, 0xffff0000, v10
	s_waitcnt lgkmcnt(1)
	v_mul_f32_e32 v1, v12, v1
	v_mul_f32_e32 v6, v13, v6
	v_mul_f32_e32 v12, v14, v8
	v_mul_f32_e32 v9, v15, v9
	v_cvt_pk_bf16_f32 v8, v1, v6
	s_waitcnt lgkmcnt(0)
	v_mul_f32_e32 v1, v17, v10
	v_mul_f32_e32 v13, v16, v20
	v_cvt_pk_bf16_f32 v9, v12, v9
	v_cvt_pk_bf16_f32 v10, v13, v1
	v_lshlrev_b32_e32 v1, 16, v11
	v_and_b32_e32 v6, 0xffff0000, v11
	v_mul_f32_e32 v1, v18, v1
	v_mul_f32_e32 v6, v19, v6
	v_cvt_pk_bf16_f32 v11, v1, v6
	global_load_dwordx4 v[12:15], v0, s[16:17]
	v_add_u32_e32 v0, s22, v224
	v_or_b32_e32 v1, s3, v0
	ds_write_b128 v183, v[8:11]
	global_load_dwordx4 v[52:55], v1, s[16:17]
	ds_read_b128 v[8:11], v229
	ds_read_b128 v[16:19], v229 offset:16
	v_or_b32_e32 v0, s33, v0
	s_waitcnt vmcnt(13)
	v_lshlrev_b32_e32 v169, 16, v97
	v_and_b32_e32 v170, 0xffff0000, v97
	v_lshlrev_b32_e32 v171, 16, v94
	v_and_b32_e32 v172, 0xffff0000, v94
	v_lshlrev_b32_e32 v173, 16, v95
	v_and_b32_e32 v174, 0xffff0000, v95
	s_waitcnt vmcnt(12)
	v_lshlrev_b32_e32 v175, 16, v92
	v_and_b32_e32 v178, 0xffff0000, v92
	v_lshlrev_b32_e32 v179, 16, v93
	v_and_b32_e32 v180, 0xffff0000, v93
	v_lshlrev_b32_e32 v181, 16, v88
	v_and_b32_e32 v184, 0xffff0000, v88
	v_lshlrev_b32_e32 v185, 16, v89
	v_and_b32_e32 v186, 0xffff0000, v89
	s_waitcnt vmcnt(11)
	v_lshlrev_b32_e32 v187, 16, v90
	v_and_b32_e32 v188, 0xffff0000, v90
	v_lshlrev_b32_e32 v189, 16, v91
	v_and_b32_e32 v204, 0xffff0000, v91
	v_lshlrev_b32_e32 v205, 16, v84
	v_and_b32_e32 v206, 0xffff0000, v84
	v_lshlrev_b32_e32 v207, 16, v85
	v_and_b32_e32 v208, 0xffff0000, v85
	s_waitcnt vmcnt(10)
	v_lshlrev_b32_e32 v209, 16, v86
	v_and_b32_e32 v210, 0xffff0000, v86
	v_lshlrev_b32_e32 v211, 16, v87
	v_and_b32_e32 v215, 0xffff0000, v87
	s_waitcnt vmcnt(1)
	v_lshlrev_b32_e32 v1, 16, v12
	v_and_b32_e32 v6, 0xffff0000, v12
	v_lshlrev_b32_e32 v12, 16, v13
	v_and_b32_e32 v13, 0xffff0000, v13
	v_lshlrev_b32_e32 v20, 16, v14
	v_and_b32_e32 v14, 0xffff0000, v14
	v_lshlrev_b32_e32 v21, 16, v15
	v_and_b32_e32 v15, 0xffff0000, v15
	s_waitcnt lgkmcnt(1)
	v_mul_f32_e32 v6, v9, v6
	v_mul_f32_e32 v9, v10, v12
	v_mul_f32_e32 v10, v11, v13
	s_waitcnt lgkmcnt(0)
	v_mul_f32_e32 v11, v16, v20
	v_mul_f32_e32 v1, v8, v1
	v_mul_f32_e32 v12, v17, v14
	v_mul_f32_e32 v13, v18, v21
	v_mul_f32_e32 v14, v19, v15
	v_cvt_pk_bf16_f32 v8, v1, v6
	v_cvt_pk_bf16_f32 v9, v9, v10
	v_cvt_pk_bf16_f32 v10, v11, v12
	v_cvt_pk_bf16_f32 v11, v13, v14
	ds_write_b128 v182, v[8:11]
	global_load_dwordx4 v[48:51], v0, s[16:17]
	s_waitcnt lgkmcnt(0)
	s_barrier
; #define LAS __attribute__((address_space(3)))
; #define MFMA32(a, b, c) __builtin_amdgcn_mfma_f32_32x32x16_bf16((a), (b), (c), 0, 0, 0)
; #define EX2(x) __builtin_amdgcn_exp2f(x)
; template <bool XW, int PASS, bool RMW> ...
;     ...
;     for (int i = 0; i < 16; ++i) { st0[i] = 0.f; st1[i] = 0.f; }
;     const float lg = pass == 0 ? lgf : lgb;
;     const float cd = EX2(lg * 128.0f);
;     const float qd = pass == 0 ? EX2(lgf * (float)(icol + 1)) : EX2(lgb * (float)(128 - icol));
;     ...
;     for (int cc = 0; cc < nc; ++cc) {
;       const int c = pass == 0 ? cc : nc - 1 - cc;
;       const int k1 = cc + 1 < nc ? cc + 1 : nc - 1, k2 = cc + 2 < nc ? cc + 2 : nc - 1;
;       const int cn = pass == 0 ? k1 : nc - 1 - k1, cnn = pass == 0 ? k2 : nc - 1 - k2;
;       if constexpr (XW) {
;         const unsigned yb = yoff0 + (unsigned)c * 524288u;
;         f32x16 yc0, yc1;
; #pragma unroll
;         for (int i = 0; i < 16; ++i) { yc0[i] = 0.f; yc1[i] = 0.f; }
;         const LAS bf16_t* sp = Sb + pbuf * SBE + r * 264 + 8 * h;
; #pragma unroll
;         for (int sb = 0; sb < 8; ++sb) {
;           bf16x8 a0[2], a1[2];
; #pragma unroll
;           for (int k = 0; k < 2; ++k) { a0[k] = *(const LAS bf16x8*)(sp + 16 * (2 * sb + k)); a1[k] = *(const LAS bf16x8*)(sp + 32 * 264 + 16 * (2 * sb + k)); }
; #pragma unroll
;           for (int k = 0; k < 2; ++k) { yc0 = MFMA32(a0[k], qf[2 * sb + k], yc0); yc1 = MFMA32(a1[k], qf[2 * sb + k], yc1); }
;         }
;         asm volatile("" : "+v"(yc0), "+v"(yc1) :: "memory");
	ds_read_b128 v[8:11], v217
	ds_read_b128 v[160:163], v217 offset:32
	s_waitcnt lgkmcnt(1)
	v_mfma_f32_32x32x16_bf16 v[8:23], v[8:11], v[24:27], 0
	ds_read_b128 v[28:31], v217 offset:16896
	ds_read_b128 v[164:167], v217 offset:16928
	v_mul_f32_e32 v0, 0xc3000000, v225
	v_exp_f32_e32 v168, v0
	s_nop 0
	v_mul_f32_e32 v0, 0, v168
	s_waitcnt lgkmcnt(1)
	v_mfma_f32_32x32x16_bf16 v[24:39], v[28:31], v[24:27], 0
	v_mov_b32_e32 v1, v0
	v_mov_b32_e32 v6, v0
	v_mfma_f32_32x32x16_bf16 v[8:23], v[160:163], v[100:103], v[8:23]
	s_waitcnt lgkmcnt(0)
	v_mfma_f32_32x32x16_bf16 v[24:39], v[164:167], v[100:103], v[24:39]
	ds_read_b128 v[100:103], v217 offset:64
	ds_read_b128 v[160:163], v217 offset:96
	s_waitcnt lgkmcnt(1)
	v_mfma_f32_32x32x16_bf16 v[8:23], v[100:103], v[104:107], v[8:23]
	ds_read_b128 v[100:103], v217 offset:16960
	ds_read_b128 v[164:167], v217 offset:16992
	s_waitcnt lgkmcnt(1)
	v_mfma_f32_32x32x16_bf16 v[24:39], v[100:103], v[104:107], v[24:39]
	ds_read_b128 v[100:103], v217 offset:128
	ds_read_b128 v[104:107], v217 offset:160
	v_mfma_f32_32x32x16_bf16 v[8:23], v[160:163], v[108:111], v[8:23]
	v_lshlrev_b32_e32 v162, 16, v98
	v_and_b32_e32 v163, 0xffff0000, v98
	s_waitcnt lgkmcnt(2)
	v_mfma_f32_32x32x16_bf16 v[24:39], v[164:167], v[108:111], v[24:39]
	v_lshlrev_b32_e32 v164, 16, v99
	v_and_b32_e32 v165, 0xffff0000, v99
	v_lshlrev_b32_e32 v166, 16, v96
	v_and_b32_e32 v167, 0xffff0000, v96
	s_waitcnt lgkmcnt(1)
	v_mfma_f32_32x32x16_bf16 v[8:23], v[100:103], v[112:115], v[8:23]
	ds_read_b128 v[100:103], v217 offset:17024
	ds_read_b128 v[108:111], v217 offset:17056
	s_waitcnt lgkmcnt(1)
	v_mfma_f32_32x32x16_bf16 v[24:39], v[100:103], v[112:115], v[24:39]
	v_add_u32_e32 v112, s23, v226
	v_or_b32_e32 v151, 0x1400, v112
	v_or_b32_e32 v160, 0x3800, v112
	v_or_b32_e32 v161, 0x3c00, v112
	v_mfma_f32_32x32x16_bf16 v[8:23], v[104:107], v[116:119], v[8:23]
	ds_read_b128 v[100:103], v217 offset:192
	ds_read_b128 v[104:107], v217 offset:224
	s_waitcnt lgkmcnt(2)
	v_mfma_f32_32x32x16_bf16 v[24:39], v[108:111], v[116:119], v[24:39]
	s_waitcnt lgkmcnt(1)
	v_mfma_f32_32x32x16_bf16 v[8:23], v[100:103], v[120:123], v[8:23]
	ds_read_b128 v[100:103], v217 offset:17088
	ds_read_b128 v[108:111], v217 offset:17120
	s_waitcnt lgkmcnt(1)
	v_mfma_f32_32x32x16_bf16 v[24:39], v[100:103], v[120:123], v[24:39]
	v_mfma_f32_32x32x16_bf16 v[8:23], v[104:107], v[124:127], v[8:23]
	ds_read_b128 v[100:103], v217 offset:256
	ds_read_b128 v[104:107], v217 offset:288
	s_waitcnt lgkmcnt(2)
	v_mfma_f32_32x32x16_bf16 v[24:39], v[108:111], v[124:127], v[24:39]
	s_waitcnt lgkmcnt(1)
	v_mfma_f32_32x32x16_bf16 v[8:23], v[100:103], v[152:155], v[8:23]
	ds_read_b128 v[100:103], v217 offset:17152
	ds_read_b128 v[108:111], v217 offset:17184
	s_waitcnt lgkmcnt(1)
	v_mfma_f32_32x32x16_bf16 v[24:39], v[100:103], v[152:155], v[24:39]
	v_or_b32_e32 v152, 0x1800, v112
	v_or_b32_e32 v153, 0x1c00, v112
	v_or_b32_e32 v154, 0x2000, v112
	v_or_b32_e32 v155, 0x2400, v112
	v_mfma_f32_32x32x16_bf16 v[8:23], v[104:107], v[156:159], v[8:23]
	ds_read_b128 v[100:103], v217 offset:320
	ds_read_b128 v[104:107], v217 offset:352
	s_waitcnt lgkmcnt(2)
	v_mfma_f32_32x32x16_bf16 v[24:39], v[108:111], v[156:159], v[24:39]
	v_or_b32_e32 v156, 0x2800, v112
	v_or_b32_e32 v157, 0x2c00, v112
	v_or_b32_e32 v158, 0x3000, v112
	v_or_b32_e32 v159, 0x3400, v112
	s_waitcnt lgkmcnt(1)
	v_mfma_f32_32x32x16_bf16 v[8:23], v[100:103], v[80:83], v[8:23]
	ds_read_b128 v[100:103], v217 offset:17216
	ds_read_b128 v[108:111], v217 offset:17248
	s_waitcnt lgkmcnt(1)
	v_mfma_f32_32x32x16_bf16 v[24:39], v[100:103], v[80:83], v[24:39]
	ds_read_b128 v[80:83], v217 offset:384
	v_mfma_f32_32x32x16_bf16 v[8:23], v[104:107], v[76:79], v[8:23]
	v_or_b32_e32 v104, 0x400, v112
	v_or_b32_e32 v105, 0x800, v112
	v_or_b32_e32 v106, 0xc00, v112
	v_or_b32_e32 v107, 0x1000, v112
	s_waitcnt lgkmcnt(1)
	v_mfma_f32_32x32x16_bf16 v[24:39], v[108:111], v[76:79], v[24:39]
	ds_read_b128 v[76:79], v217 offset:17280
	ds_read_b128 v[100:103], v217 offset:416
	s_waitcnt lgkmcnt(2)
	v_mfma_f32_32x32x16_bf16 v[8:23], v[80:83], v[2:5], v[8:23]
	ds_read_b128 v[80:83], v217 offset:17312
	s_waitcnt lgkmcnt(2)
	v_mfma_f32_32x32x16_bf16 v[24:39], v[76:79], v[2:5], v[24:39]
	ds_read_b128 v[76:79], v217 offset:448
	v_mov_b32_e32 v2, v0
	v_mov_b32_e32 v3, v0
	v_mov_b32_e32 v4, v0
	v_mov_b32_e32 v5, v0
	s_waitcnt lgkmcnt(2)
	v_mfma_f32_32x32x16_bf16 v[8:23], v[100:103], v[72:75], v[8:23]
	s_waitcnt lgkmcnt(1)
	v_mfma_f32_32x32x16_bf16 v[24:39], v[80:83], v[72:75], v[24:39]
	ds_read_b128 v[72:75], v217 offset:17344
	ds_read_b128 v[80:83], v217 offset:480
	s_waitcnt lgkmcnt(2)
	v_mfma_f32_32x32x16_bf16 v[8:23], v[76:79], v[68:71], v[8:23]
	ds_read_b128 v[76:79], v217 offset:17376
	s_waitcnt lgkmcnt(2)
	v_mfma_f32_32x32x16_bf16 v[24:39], v[72:75], v[68:71], v[24:39]
	s_waitcnt lgkmcnt(1)
	v_mfma_f32_32x32x16_bf16 v[8:23], v[80:83], v[64:67], v[8:23]
	s_waitcnt lgkmcnt(0)
; #define LAS __attribute__((address_space(3)))
; DI unsigned cvt_pk_bf16(float lo, float hi) { unsigned r; asm volatile("v_cvt_pk_bf16_f32 %0, %1, %2" : "=v"(r) : "v"(lo), "v"(hi)); return r; }
; DI float bf_lo(unsigned w) { return __uint_as_float(w << 16); }
; DI float bf_hi(unsigned w) { return __uint_as_float(w & 0xffff0000u); }
; #define MFMA32(a, b, c) __builtin_amdgcn_mfma_f32_32x32x16_bf16((a), (b), (c), 0, 0, 0)
; template <bool XW, int PASS, bool RMW> ...
;     ...
; #pragma unroll
;         for (int s = 0; s < 16; ++s) qf[s] = ldg16(qr, qoff0 + (unsigned)cn * 262144u + 1024u * s);
;         const float qe = cc > 0 ? qd : 0.f;
; #pragma unroll
;         for (int gq = 0; gq < 4; ++gq) {
;           u32x2 a; a.x = cvt_pk_bf16(bf_lo(ovn[gq].x) + qe * yc0[4 * gq], bf_hi(ovn[gq].x) + qe * yc0[4 * gq + 1]); a.y = cvt_pk_bf16(bf_lo(ovn[gq].y) + qe * yc0[4 * gq + 2], bf_hi(ovn[gq].y) + qe * yc0[4 * gq + 3]);
;           *(u32x2*)((char*)y + (yb + 16u * gq)) = a;
;           u32x2 c2; c2.x = cvt_pk_bf16(bf_lo(ovn[4 + gq].x) + qe * yc1[4 * gq], bf_hi(ovn[4 + gq].x) + qe * yc1[4 * gq + 1]); c2.y = cvt_pk_bf16(bf_lo(ovn[4 + gq].y) + qe * yc1[4 * gq + 2], bf_hi(ovn[4 + gq].y) + qe * yc1[4 * gq + 3]);
;           *(u32x2*)((char*)y + (yb + 64u + 16u * gq)) = c2;
;         }
;         if constexpr (PASS == 1 && RMW) {
;           const unsigned ybn = yoff0 + (unsigned)cn * 524288u;
; #pragma unroll
;           for (int gq = 0; gq < 8; ++gq) ovn[gq] = *(const u32x2*)((const char*)y + (ybn + 64u * (gq >> 2) + 16u * (gq & 3)));
;         }
;       }
; #pragma unroll
;       for (int i = 0; i < 16; ++i) { st0[i] *= cd; st1[i] *= cd; }
; #pragma unroll
;       for (int sb = 0; sb < 2; ++sb) {
;         bf16x8 a0[4], a1[4];
; #pragma unroll
;         for (int k = 0; k < 4; ++k) { a0[k] = *(const LAS bf16x8*)(vimg + (cc & 1) * 16384 + (4 * sb + k) * 1024 + lane * 16); a1[k] = *(const LAS bf16x8*)(vimg + (cc & 1) * 16384 + 8192 + (4 * sb + k) * 1024 + lane * 16); }
; #pragma unroll
;         for (int k = 0; k < 4; ++k) { st0 = MFMA32(a0[k], kb0[4 * sb + k], st0); st1 = MFMA32(a1[k], kb0[4 * sb + k], st1); }
;         asm volatile("" : "+v"(st0), "+v"(st1) :: "memory");
; #pragma unroll
;         for (int k = 0; k < 4; ++k) kb0[4 * sb + k] = ldg16(kT, kboff0 + (unsigned)cn * 262144u + 1024u * (4 * sb + k));
;       }
	v_mfma_f32_32x32x16_bf16 v[24:39], v[76:79], v[64:67], v[24:39]
	global_load_dwordx4 v[120:123], v112, s[92:93]
	global_load_dwordx4 v[124:127], v104, s[92:93]
	s_nop 0
	global_load_dwordx4 v[112:115], v105, s[92:93]
	global_load_dwordx4 v[116:119], v106, s[92:93]
	s_nop 0
	global_load_dwordx4 v[104:107], v107, s[92:93]
	s_nop 0
	global_load_dwordx4 v[108:111], v151, s[92:93]
	global_load_dwordx4 v[96:99], v152, s[92:93]
	global_load_dwordx4 v[100:103], v153, s[92:93]
	global_load_dwordx4 v[88:91], v154, s[92:93]
	global_load_dwordx4 v[92:95], v155, s[92:93]
	global_load_dwordx4 v[80:83], v156, s[92:93]
	global_load_dwordx4 v[84:87], v157, s[92:93]
	global_load_dwordx4 v[72:75], v158, s[92:93]
	global_load_dwordx4 v[76:79], v159, s[92:93]
	global_load_dwordx4 v[64:67], v160, s[92:93]
	global_load_dwordx4 v[68:71], v161, s[92:93]
	v_fmac_f32_e32 v162, 0, v8
	v_fmac_f32_e32 v163, 0, v9
	v_fmac_f32_e32 v164, 0, v10
	v_fmac_f32_e32 v165, 0, v11
	v_cvt_pk_bf16_f32 v8, v162, v163
	v_cvt_pk_bf16_f32 v9, v164, v165
	v_fmac_f32_e32 v166, 0, v24
	v_fmac_f32_e32 v167, 0, v25
	v_fmac_f32_e32 v169, 0, v26
	v_fmac_f32_e32 v170, 0, v27
	global_store_dwordx2 v7, v[8:9], s[18:19]
	v_cvt_pk_bf16_f32 v8, v166, v167
	v_cvt_pk_bf16_f32 v9, v169, v170
	v_fmac_f32_e32 v171, 0, v12
	v_fmac_f32_e32 v172, 0, v13
	v_fmac_f32_e32 v173, 0, v14
	v_fmac_f32_e32 v174, 0, v15
	global_store_dwordx2 v150, v[8:9], s[18:19]
	v_cvt_pk_bf16_f32 v8, v171, v172
	v_cvt_pk_bf16_f32 v9, v173, v174
	v_fmac_f32_e32 v175, 0, v28
	v_fmac_f32_e32 v178, 0, v29
	v_fmac_f32_e32 v179, 0, v30
	v_fmac_f32_e32 v180, 0, v31
	global_store_dwordx2 v148, v[8:9], s[18:19]
	v_cvt_pk_bf16_f32 v8, v175, v178
	v_cvt_pk_bf16_f32 v9, v179, v180
	v_fmac_f32_e32 v181, 0, v16
	v_fmac_f32_e32 v184, 0, v17
	v_fmac_f32_e32 v185, 0, v18
	v_fmac_f32_e32 v186, 0, v19
	global_store_dwordx2 v149, v[8:9], s[18:19]
	v_cvt_pk_bf16_f32 v8, v181, v184
	v_cvt_pk_bf16_f32 v9, v185, v186
	v_fmac_f32_e32 v187, 0, v32
	v_fmac_f32_e32 v188, 0, v33
	v_fmac_f32_e32 v189, 0, v34
	v_fmac_f32_e32 v204, 0, v35
	global_store_dwordx2 v146, v[8:9], s[18:19]
	v_cvt_pk_bf16_f32 v8, v187, v188
	v_cvt_pk_bf16_f32 v9, v189, v204
	v_fmac_f32_e32 v205, 0, v20
	v_fmac_f32_e32 v206, 0, v21
	v_fmac_f32_e32 v207, 0, v22
	v_fmac_f32_e32 v208, 0, v23
	v_fmac_f32_e32 v209, 0, v36
	v_fmac_f32_e32 v210, 0, v37
	v_fmac_f32_e32 v211, 0, v38
	v_fmac_f32_e32 v215, 0, v39
	global_store_dwordx2 v147, v[8:9], s[18:19]
	v_cvt_pk_bf16_f32 v8, v205, v206
	v_cvt_pk_bf16_f32 v9, v207, v208
	global_store_dwordx2 v145, v[8:9], s[18:19]
	v_cvt_pk_bf16_f32 v150, v209, v210
	v_cvt_pk_bf16_f32 v151, v211, v215
	ds_read_b128 v[32:35], v231
	ds_read_b128 v[36:39], v231 offset:1024
	v_mov_b32_e32 v7, v0
	v_mov_b32_e32 v8, v0
	v_mov_b32_e32 v9, v0
	v_mov_b32_e32 v10, v0
	v_mov_b32_e32 v11, v0
	v_mov_b32_e32 v12, v0
	v_mov_b32_e32 v13, v0
	v_mov_b32_e32 v14, v0
	v_mov_b32_e32 v15, v0
	s_waitcnt vmcnt(24)
	v_lshlrev_b32_e32 v160, 16, v52
	v_and_b32_e32 v52, 0xffff0000, v52
	s_waitcnt lgkmcnt(1)
	v_mfma_f32_32x32x16_bf16 v[16:31], v[32:35], v[132:135], v[0:15]
	ds_read_b128 v[32:35], v230
	ds_read_b128 v[146:149], v230 offset:1024
	v_lshlrev_b32_e32 v161, 16, v53
	v_and_b32_e32 v53, 0xffff0000, v53
	s_waitcnt lgkmcnt(2)
	v_mfma_f32_32x32x16_bf16 v[16:31], v[36:39], v[140:143], v[16:31]
	s_waitcnt lgkmcnt(1)
	v_mfma_f32_32x32x16_bf16 v[0:15], v[32:35], v[132:135], v[0:15]
	ds_read_b128 v[32:35], v231 offset:2048
	ds_read_b128 v[36:39], v231 offset:3072
	ds_read_b128 v[132:135], v230 offset:3072
	global_store_dwordx2 v144, v[150:151], s[18:19]
	s_waitcnt lgkmcnt(2)
	v_mfma_f32_32x32x16_bf16 v[16:31], v[32:35], v[136:139], v[16:31]
	ds_read_b128 v[32:35], v230 offset:2048
	v_mfma_f32_32x32x16_bf16 v[0:15], v[146:149], v[140:143], v[0:15]
	v_add_u32_e32 v140, s24, v227
	v_or_b32_e32 v141, 16, v140
	s_waitcnt lgkmcnt(0)
	v_mfma_f32_32x32x16_bf16 v[0:15], v[32:35], v[136:139], v[0:15]
	v_or_b32_e32 v32, 32, v140
	v_or_b32_e32 v33, 48, v140
	global_load_dwordx2 v[188:189], v140, s[18:19]
	global_load_dwordx2 v[184:185], v141, s[18:19]
	global_load_dwordx2 v[178:179], v32, s[18:19]
	global_load_dwordx2 v[172:173], v33, s[18:19]
	v_or_b32_e32 v32, 64, v140
	v_or_b32_e32 v33, 0x50, v140
	v_or_b32_e32 v34, 0x60, v140
	v_or_b32_e32 v35, 0x70, v140
	v_mfma_f32_32x32x16_bf16 v[16:31], v[36:39], v[128:131], v[16:31]
	global_load_dwordx2 v[186:187], v32, s[18:19]
	global_load_dwordx2 v[180:181], v33, s[18:19]
	global_load_dwordx2 v[174:175], v34, s[18:19]
	global_load_dwordx2 v[170:171], v35, s[18:19]
	v_mfma_f32_32x32x16_bf16 v[0:15], v[132:135], v[128:131], v[0:15]
	ds_read_b128 v[32:35], v231 offset:4096
	ds_read_b128 v[36:39], v231 offset:5120
	s_waitcnt lgkmcnt(1)
	v_mfma_f32_32x32x16_bf16 v[16:31], v[32:35], v[60:63], v[16:31]
	ds_read_b128 v[32:35], v230 offset:4096
	ds_read_b128 v[128:131], v230 offset:5120
	s_waitcnt lgkmcnt(2)
	v_mfma_f32_32x32x16_bf16 v[16:31], v[36:39], v[56:59], v[16:31]
	s_waitcnt lgkmcnt(1)
	v_mfma_f32_32x32x16_bf16 v[0:15], v[32:35], v[60:63], v[0:15]
	ds_read_b128 v[32:35], v231 offset:6144
	ds_read_b128 v[36:39], v231 offset:7168
	v_add_u32_e32 v60, s23, v223
	v_or_b32_e32 v62, 0x400, v60
	v_or_b32_e32 v63, 0x800, v60
	v_add_u32_e32 v61, s25, v224
	v_add3_u32 v231, v222, v203, s2
	s_mov_b32 s2, 1
	s_waitcnt lgkmcnt(1)
	v_mfma_f32_32x32x16_bf16 v[16:31], v[32:35], v[44:47], v[16:31]
	ds_read_b128 v[32:35], v230 offset:6144
	v_mfma_f32_32x32x16_bf16 v[0:15], v[128:131], v[56:59], v[0:15]
	ds_read_b128 v[56:59], v230 offset:7168
	s_waitcnt lgkmcnt(1)
; #define LAS __attribute__((address_space(3)))
; DI unsigned cvt_pk_bf16(float lo, float hi) { unsigned r; asm volatile("v_cvt_pk_bf16_f32 %0, %1, %2" : "=v"(r) : "v"(lo), "v"(hi)); return r; }
; #define MFMA32(a, b, c) __builtin_amdgcn_mfma_f32_32x32x16_bf16((a), (b), (c), 0, 0, 0)
; template <bool XW, int PASS, bool RMW> ...
;     ...
;         for (int k = 0; k < 4; ++k) { st0 = MFMA32(a0[k], kb0[4 * sb + k], st0); st1 = MFMA32(a1[k], kb0[4 * sb + k], st1); }
;         asm volatile("" : "+v"(st0), "+v"(st1) :: "memory");
; #pragma unroll
;         for (int k = 0; k < 4; ++k) kb0[4 * sb + k] = ldg16(kT, kboff0 + (unsigned)cn * 262144u + 1024u * (4 * sb + k));
;       }
; #pragma unroll
;       for (int t = 0; t < 2; ++t) {
;         const int sv = 2 * dq + t;
;         *(LAS bf16x8*)(vimg + ((cc + 1) & 1) * 16384 + et * 8192 + sv * 1024 + lane * 16) = scale_tab(vr[t], kdec + 16 * sv + 8 * h);
;         vr[t] = ldg16(vT, vaoff0 + (unsigned)cnn * 524288u + 1024u * sv);
;       }
;       LAS bf16_t* sw = Sb + (pbuf ^ 1) * SBE + (4 * h) * 264 + 32 * w + r;
; #pragma unroll
;       for (int i = 0; i < 16; ++i) {
;         const int eo = ((i & 3) + 8 * (i >> 2)) * 264;
;         const unsigned pkw = cvt_pk_bf16(st0[i], st1[i]);
;         sw[eo] = (bf16_t)(pkw & 0xffffu);
;         sw[eo + 32 * 264] = (bf16_t)(pkw >> 16);
;       }
;       lds_barrier();
;       pbuf ^= 1;
	v_mfma_f32_32x32x16_bf16 v[0:15], v[32:35], v[44:47], v[0:15]
	v_or_b32_e32 v32, 0xc00, v60
	global_load_dwordx4 v[128:131], v60, s[14:15]
	global_load_dwordx4 v[132:135], v62, s[14:15]
	global_load_dwordx4 v[136:139], v63, s[14:15]
	global_load_dwordx4 v[140:143], v32, s[14:15]
	v_or_b32_e32 v44, 0x1000, v60
	v_or_b32_e32 v45, 0x1400, v60
	v_or_b32_e32 v46, 0x1800, v60
	v_or_b32_e32 v47, 0x1c00, v60
	v_lshlrev_b32_e32 v60, 16, v54
	v_mfma_f32_32x32x16_bf16 v[16:31], v[36:39], v[40:43], v[16:31]
	s_waitcnt lgkmcnt(0)
	v_mfma_f32_32x32x16_bf16 v[0:15], v[56:59], v[40:43], v[0:15]
	ds_read_b128 v[32:35], v228
	global_load_dwordx4 v[144:147], v44, s[14:15]
	global_load_dwordx4 v[148:151], v45, s[14:15]
	global_load_dwordx4 v[152:155], v46, s[14:15]
	global_load_dwordx4 v[156:159], v47, s[14:15]
	ds_read_b128 v[36:39], v228 offset:16
	s_waitcnt vmcnt(40)
	v_lshlrev_b32_e32 v40, 16, v48
	s_waitcnt lgkmcnt(1)
	v_mul_f32_e32 v32, v32, v160
	v_mul_f32_e32 v33, v33, v52
	v_mul_f32_e32 v35, v35, v53
	v_mul_f32_e32 v34, v34, v161
	v_cvt_pk_bf16_f32 v32, v32, v33
	v_cvt_pk_bf16_f32 v33, v34, v35
	v_and_b32_e32 v35, 0xffff0000, v54
	s_waitcnt lgkmcnt(0)
	v_mul_f32_e32 v34, v36, v60
	v_mul_f32_e32 v35, v37, v35
	v_cvt_pk_bf16_f32 v34, v34, v35
	v_lshlrev_b32_e32 v35, 16, v55
	v_mul_f32_e32 v35, v38, v35
	v_and_b32_e32 v36, 0xffff0000, v55
	v_mul_f32_e32 v36, v39, v36
	v_cvt_pk_bf16_f32 v35, v35, v36
	ds_write_b128 v183, v[32:35] offset:16384
	ds_read_b128 v[32:35], v229
	v_or_b32_e32 v36, s3, v61
	global_load_dwordx4 v[160:163], v36, s[16:17]
	ds_read_b128 v[36:39], v229 offset:16
	v_mov_b32_e32 v183, v168
	s_waitcnt lgkmcnt(1)
	v_mul_f32_e32 v32, v32, v40
	v_and_b32_e32 v40, 0xffff0000, v48
	v_mul_f32_e32 v33, v33, v40
	v_cvt_pk_bf16_f32 v32, v32, v33
	v_lshlrev_b32_e32 v33, 16, v49
	v_mul_f32_e32 v33, v34, v33
	v_and_b32_e32 v34, 0xffff0000, v49
	v_mul_f32_e32 v34, v35, v34
	v_cvt_pk_bf16_f32 v33, v33, v34
	v_lshlrev_b32_e32 v34, 16, v50
	v_and_b32_e32 v35, 0xffff0000, v50
	s_waitcnt lgkmcnt(0)
	v_mul_f32_e32 v34, v36, v34
	v_mul_f32_e32 v35, v37, v35
	v_cvt_pk_bf16_f32 v34, v34, v35
	v_lshlrev_b32_e32 v35, 16, v51
	v_and_b32_e32 v36, 0xffff0000, v51
	v_mul_f32_e32 v35, v38, v35
	v_mul_f32_e32 v36, v39, v36
	v_cvt_pk_bf16_f32 v35, v35, v36
	v_or_b32_e32 v36, s33, v61
	global_load_dwordx4 v[164:167], v36, s[16:17]
	ds_write_b128 v182, v[32:35] offset:16384
	v_cvt_pk_bf16_f32 v32, v16, v0
	ds_write_b16 v199, v32 offset:33792
	ds_write_b16_d16_hi v199, v32 offset:50688
	v_cvt_pk_bf16_f32 v32, v17, v1
	ds_write_b16 v199, v32 offset:34320
	ds_write_b16_d16_hi v199, v32 offset:51216
	v_cvt_pk_bf16_f32 v32, v18, v2
	ds_write_b16 v199, v32 offset:34848
	ds_write_b16_d16_hi v199, v32 offset:51744
	v_cvt_pk_bf16_f32 v32, v19, v3
	ds_write_b16 v199, v32 offset:35376
	ds_write_b16_d16_hi v199, v32 offset:52272
	v_cvt_pk_bf16_f32 v32, v20, v4
	ds_write_b16 v199, v32 offset:38016
	ds_write_b16_d16_hi v199, v32 offset:54912
	v_cvt_pk_bf16_f32 v32, v21, v5
	ds_write_b16 v199, v32 offset:38544
	ds_write_b16_d16_hi v199, v32 offset:55440
	v_cvt_pk_bf16_f32 v32, v22, v6
	ds_write_b16 v199, v32 offset:39072
	ds_write_b16_d16_hi v199, v32 offset:55968
	v_cvt_pk_bf16_f32 v32, v23, v7
	ds_write_b16 v199, v32 offset:39600
	ds_write_b16_d16_hi v199, v32 offset:56496
	v_cvt_pk_bf16_f32 v32, v24, v8
	ds_write_b16 v199, v32 offset:42240
	ds_write_b16_d16_hi v199, v32 offset:59136
	v_cvt_pk_bf16_f32 v32, v25, v9
	ds_write_b16 v199, v32 offset:42768
	ds_write_b16_d16_hi v199, v32 offset:59664
	v_cvt_pk_bf16_f32 v32, v26, v10
	ds_write_b16 v199, v32 offset:43296
	ds_write_b16_d16_hi v199, v32 offset:60192
	v_cvt_pk_bf16_f32 v32, v27, v11
	ds_write_b16 v199, v32 offset:43824
	ds_write_b16_d16_hi v199, v32 offset:60720
	v_cvt_pk_bf16_f32 v32, v28, v12
	ds_write_b16 v199, v32 offset:46464
	ds_write_b16_d16_hi v199, v32 offset:63360
	v_cvt_pk_bf16_f32 v32, v29, v13
	ds_write_b16 v199, v32 offset:46992
	ds_write_b16_d16_hi v199, v32 offset:63888
	v_cvt_pk_bf16_f32 v32, v30, v14
	v_mul_f32_e64 v36, v219, -v225
	ds_write_b16 v199, v32 offset:47520
	ds_write_b16_d16_hi v199, v32 offset:64416
	v_cvt_pk_bf16_f32 v32, v31, v15
	v_exp_f32_e32 v230, v36
	ds_write_b16 v199, v32 offset:48048
	ds_write_b16_d16_hi v199, v32 offset:64944
	s_waitcnt lgkmcnt(0)
	s_barrier
	v_mov_b32_e32 v182, v168
	s_mov_b32 s101, 0
.LBB0_102:
	s_cmp_eq_u32 s101, 0
	s_cbranch_scc1 .Lrmw_skip
	s_waitcnt vmcnt(10)
	ds_write_b128 v253, v[172:175]
	ds_write_b128 v253, v[184:187] offset:1088
	ds_write_b128 v253, v[178:181] offset:2176
	ds_write_b128 v253, v[208:211] offset:3264
	s_waitcnt lgkmcnt(0)
	ds_read_b64 v[188:189], v252
	ds_read_b64 v[184:185], v252 offset:16
	ds_read_b64 v[178:179], v252 offset:32
	ds_read_b64 v[172:173], v252 offset:48
	ds_read_b64 v[186:187], v252 offset:64
	ds_read_b64 v[180:181], v252 offset:80
	ds_read_b64 v[174:175], v252 offset:96
	ds_read_b64 v[170:171], v252 offset:112
	s_waitcnt lgkmcnt(0)
; #define LAS __attribute__((address_space(3)))
; #define MFMA32(a, b, c) __builtin_amdgcn_mfma_f32_32x32x16_bf16((a), (b), (c), 0, 0, 0)
; template <bool XW, int PASS, bool RMW> ...
;     ...
;     for (int cc = 0; cc < nc; ++cc) {
;       const int c = pass == 0 ? cc : nc - 1 - cc;
;       const int k1 = cc + 1 < nc ? cc + 1 : nc - 1, k2 = cc + 2 < nc ? cc + 2 : nc - 1;
;       const int cn = pass == 0 ? k1 : nc - 1 - k1, cnn = pass == 0 ? k2 : nc - 1 - k2;
;       if constexpr (XW) {
;         const unsigned yb = yoff0 + (unsigned)c * 524288u;
;         f32x16 yc0, yc1;
; #pragma unroll
;         for (int i = 0; i < 16; ++i) { yc0[i] = 0.f; yc1[i] = 0.f; }
;         const LAS bf16_t* sp = Sb + pbuf * SBE + r * 264 + 8 * h;
; #pragma unroll
;         for (int sb = 0; sb < 8; ++sb) {
;           bf16x8 a0[2], a1[2];
; #pragma unroll
;           for (int k = 0; k < 2; ++k) { a0[k] = *(const LAS bf16x8*)(sp + 16 * (2 * sb + k)); a1[k] = *(const LAS bf16x8*)(sp + 32 * 264 + 16 * (2 * sb + k)); }
; #pragma unroll
;           for (int k = 0; k < 2; ++k) { yc0 = MFMA32(a0[k], qf[2 * sb + k], yc0); yc1 = MFMA32(a1[k], qf[2 * sb + k], yc1); }
;         }
;         asm volatile("" : "+v"(yc0), "+v"(yc1) :: "memory");
.Lrmw_skip:
	s_add_i32 s8, s2, 1
	v_mov_b32_e32 v32, s8
	s_add_i32 s2, s2, 2
	v_sub_u32_e64 v169, s5, v32 clamp
	v_mov_b32_e32 v32, s2
	s_mul_i32 s2, s0, 0x8400
	v_add_u32_e32 v204, s2, v217
	v_sub_u32_e64 v203, s5, v32 clamp
	ds_read_b128 v[232:235], v204
	ds_read_b128 v[236:239], v204 offset:16896
	ds_read_b128 v[240:243], v204 offset:32
	ds_read_b128 v[244:247], v204 offset:16928
	ds_read_b128 v[248:251], v204 offset:64
	s_waitcnt vmcnt(33)
	s_waitcnt lgkmcnt(4)
	v_mfma_f32_32x32x16_bf16 v[48:63], v[232:235], v[120:123], 0
	ds_read_b128 v[232:235], v204 offset:16960
	v_lshlrev_b32_e32 v206, 18, v169
	s_waitcnt vmcnt(10)
	v_lshlrev_b32_e32 v205, 16, v188
	s_and_b32 s2, s1, 0x4000
	v_mul_f32_e64 v16, v182, v16
	v_mul_f32_e64 v17, v183, v17
	v_pk_mul_f32 v[0:1], v[182:183], v[0:1]
	s_addk_i32 s1, 0x4000
	s_xor_b32 s0, s0, 1
	s_waitcnt lgkmcnt(4)
	v_mfma_f32_32x32x16_bf16 v[32:47], v[236:239], v[120:123], 0
	ds_read_b128 v[236:239], v204 offset:96
	ds_read_b128 v[120:123], v204 offset:16992
	s_waitcnt lgkmcnt(5)
	v_mfma_f32_32x32x16_bf16 v[48:63], v[240:243], v[124:127], v[48:63]
	ds_read_b128 v[240:243], v204 offset:128
	s_waitcnt lgkmcnt(5)
	v_mfma_f32_32x32x16_bf16 v[32:47], v[244:247], v[124:127], v[32:47]
	ds_read_b128 v[244:247], v204 offset:17024
	ds_read_b128 v[124:127], v204 offset:160
	s_waitcnt lgkmcnt(6)
	v_mfma_f32_32x32x16_bf16 v[48:63], v[248:251], v[112:115], v[48:63]
	ds_read_b128 v[248:251], v204 offset:17056
	s_waitcnt lgkmcnt(6)
	v_mfma_f32_32x32x16_bf16 v[32:47], v[232:235], v[112:115], v[32:47]
	ds_read_b128 v[232:235], v204 offset:192
	ds_read_b128 v[112:115], v204 offset:17088
	s_waitcnt lgkmcnt(7)
	v_mfma_f32_32x32x16_bf16 v[48:63], v[236:239], v[116:119], v[48:63]
	ds_read_b128 v[236:239], v204 offset:224
	s_waitcnt lgkmcnt(7)
	v_mfma_f32_32x32x16_bf16 v[32:47], v[120:123], v[116:119], v[32:47]
	ds_read_b128 v[120:123], v204 offset:17120
	s_waitcnt lgkmcnt(7)
	v_mfma_f32_32x32x16_bf16 v[48:63], v[240:243], v[104:107], v[48:63]
	ds_read_b128 v[240:243], v204 offset:256
	s_waitcnt lgkmcnt(7)
	v_mfma_f32_32x32x16_bf16 v[32:47], v[244:247], v[104:107], v[32:47]
	ds_read_b128 v[244:247], v204 offset:17152
	s_waitcnt lgkmcnt(7)
	v_mfma_f32_32x32x16_bf16 v[48:63], v[124:127], v[108:111], v[48:63]
	ds_read_b128 v[124:127], v204 offset:288
	s_waitcnt lgkmcnt(7)
	v_mfma_f32_32x32x16_bf16 v[32:47], v[248:251], v[108:111], v[32:47]
	ds_read_b128 v[248:251], v204 offset:17184
	s_waitcnt lgkmcnt(7)
	v_mfma_f32_32x32x16_bf16 v[48:63], v[232:235], v[96:99], v[48:63]
	ds_read_b128 v[232:235], v204 offset:320
	s_waitcnt lgkmcnt(7)
	v_mfma_f32_32x32x16_bf16 v[32:47], v[112:115], v[96:99], v[32:47]
	ds_read_b128 v[112:115], v204 offset:17216
	s_waitcnt lgkmcnt(7)
	v_mfma_f32_32x32x16_bf16 v[48:63], v[236:239], v[100:103], v[48:63]
	ds_read_b128 v[236:239], v204 offset:352
	s_waitcnt lgkmcnt(7)
	v_mfma_f32_32x32x16_bf16 v[32:47], v[120:123], v[100:103], v[32:47]
	ds_read_b128 v[120:123], v204 offset:17248
	s_waitcnt lgkmcnt(7)
	v_mfma_f32_32x32x16_bf16 v[48:63], v[240:243], v[88:91], v[48:63]
	ds_read_b128 v[240:243], v204 offset:384
	s_waitcnt lgkmcnt(7)
	v_mfma_f32_32x32x16_bf16 v[32:47], v[244:247], v[88:91], v[32:47]
	ds_read_b128 v[244:247], v204 offset:17280
	s_waitcnt lgkmcnt(7)
	v_mfma_f32_32x32x16_bf16 v[48:63], v[124:127], v[92:95], v[48:63]
	ds_read_b128 v[124:127], v204 offset:416
	s_waitcnt lgkmcnt(7)
	v_mfma_f32_32x32x16_bf16 v[32:47], v[248:251], v[92:95], v[32:47]
	ds_read_b128 v[248:251], v204 offset:17312
	s_waitcnt lgkmcnt(7)
	v_mfma_f32_32x32x16_bf16 v[48:63], v[232:235], v[80:83], v[48:63]
	ds_read_b128 v[232:235], v204 offset:448
	s_waitcnt lgkmcnt(7)
	v_mfma_f32_32x32x16_bf16 v[32:47], v[112:115], v[80:83], v[32:47]
	ds_read_b128 v[112:115], v204 offset:17344
	s_waitcnt lgkmcnt(7)
	v_mfma_f32_32x32x16_bf16 v[48:63], v[236:239], v[84:87], v[48:63]
	ds_read_b128 v[236:239], v204 offset:480
	s_waitcnt lgkmcnt(7)
	v_mfma_f32_32x32x16_bf16 v[32:47], v[120:123], v[84:87], v[32:47]
	ds_read_b128 v[120:123], v204 offset:17376
	s_waitcnt lgkmcnt(7)
	v_mfma_f32_32x32x16_bf16 v[48:63], v[240:243], v[72:75], v[48:63]
	s_waitcnt lgkmcnt(6)
	v_mfma_f32_32x32x16_bf16 v[32:47], v[244:247], v[72:75], v[32:47]
	s_waitcnt lgkmcnt(5)
	v_mfma_f32_32x32x16_bf16 v[48:63], v[124:127], v[76:79], v[48:63]
	s_waitcnt lgkmcnt(4)
	v_mfma_f32_32x32x16_bf16 v[32:47], v[248:251], v[76:79], v[32:47]
	v_add_u32_e32 v204, 64, v231
	s_waitcnt lgkmcnt(3)
	v_mfma_f32_32x32x16_bf16 v[48:63], v[232:235], v[64:67], v[48:63]
	s_waitcnt lgkmcnt(2)
	v_mfma_f32_32x32x16_bf16 v[32:47], v[112:115], v[64:67], v[32:47]
	s_waitcnt lgkmcnt(1)
	v_mfma_f32_32x32x16_bf16 v[48:63], v[236:239], v[68:71], v[48:63]
	s_waitcnt lgkmcnt(0)
; DI unsigned cvt_pk_bf16(float lo, float hi) { unsigned r; asm volatile("v_cvt_pk_bf16_f32 %0, %1, %2" : "=v"(r) : "v"(lo), "v"(hi)); return r; }
; DI float bf_lo(unsigned w) { return __uint_as_float(w << 16); }
; DI float bf_hi(unsigned w) { return __uint_as_float(w & 0xffff0000u); }
; template <bool XW, int PASS, bool RMW> ...
;     ...
; #pragma unroll
;         for (int s = 0; s < 16; ++s) qf[s] = ldg16(qr, qoff0 + (unsigned)cn * 262144u + 1024u * s);
;         const float qe = cc > 0 ? qd : 0.f;
; #pragma unroll
;         for (int gq = 0; gq < 4; ++gq) {
;           u32x2 a; a.x = cvt_pk_bf16(bf_lo(ovn[gq].x) + qe * yc0[4 * gq], bf_hi(ovn[gq].x) + qe * yc0[4 * gq + 1]); a.y = cvt_pk_bf16(bf_lo(ovn[gq].y) + qe * yc0[4 * gq + 2], bf_hi(ovn[gq].y) + qe * yc0[4 * gq + 3]);
;           *(u32x2*)((char*)y + (yb + 16u * gq)) = a;
;           u32x2 c2; c2.x = cvt_pk_bf16(bf_lo(ovn[4 + gq].x) + qe * yc1[4 * gq], bf_hi(ovn[4 + gq].x) + qe * yc1[4 * gq + 1]); c2.y = cvt_pk_bf16(bf_lo(ovn[4 + gq].y) + qe * yc1[4 * gq + 2], bf_hi(ovn[4 + gq].y) + qe * yc1[4 * gq + 3]);
;           *(u32x2*)((char*)y + (yb + 64u + 16u * gq)) = c2;
;         }
	v_mfma_f32_32x32x16_bf16 v[32:47], v[120:123], v[68:71], v[32:47]
	v_add_u32_e32 v68, v206, v226
	v_or_b32_e32 v64, 0x400, v68
	global_load_dwordx4 v[120:123], v68, s[92:93]
	global_load_dwordx4 v[124:127], v64, s[92:93]
	v_or_b32_e32 v64, 0x800, v68
	global_load_dwordx4 v[112:115], v64, s[92:93]
	v_or_b32_e32 v64, 0xc00, v68
	global_load_dwordx4 v[116:119], v64, s[92:93]
	v_or_b32_e32 v64, 0x1000, v68
	global_load_dwordx4 v[104:107], v64, s[92:93]
	v_or_b32_e32 v64, 0x1400, v68
	global_load_dwordx4 v[108:111], v64, s[92:93]
	v_or_b32_e32 v64, 0x1800, v68
	global_load_dwordx4 v[96:99], v64, s[92:93]
	v_or_b32_e32 v64, 0x1c00, v68
	global_load_dwordx4 v[100:103], v64, s[92:93]
	v_or_b32_e32 v64, 0x2000, v68
	global_load_dwordx4 v[88:91], v64, s[92:93]
	v_or_b32_e32 v64, 0x2400, v68
	global_load_dwordx4 v[92:95], v64, s[92:93]
	v_or_b32_e32 v64, 0x2800, v68
	global_load_dwordx4 v[80:83], v64, s[92:93]
	v_or_b32_e32 v64, 0x2c00, v68
	global_load_dwordx4 v[84:87], v64, s[92:93]
	v_or_b32_e32 v64, 0x3000, v68
	global_load_dwordx4 v[72:75], v64, s[92:93]
	v_or_b32_e32 v64, 0x3400, v68
	v_fmac_f32_e32 v205, v230, v48
	v_and_b32_e32 v48, 0xffff0000, v188
	global_load_dwordx4 v[76:79], v64, s[92:93]
	v_or_b32_e32 v64, 0x3800, v68
	v_or_b32_e32 v68, 0x3c00, v68
	v_fmac_f32_e32 v48, v230, v49
	v_lshlrev_b32_e32 v49, 16, v189
	global_load_dwordx4 v[64:67], v64, s[92:93]
	v_fmac_f32_e32 v49, v230, v50
	global_load_dwordx4 v[68:71], v68, s[92:93]
	v_cvt_pk_bf16_f32 v48, v205, v48
	v_and_b32_e32 v50, 0xffff0000, v189
	v_fmac_f32_e32 v50, v230, v51
	v_cvt_pk_bf16_f32 v49, v49, v50
	v_mbcnt_lo_u32_b32 v240, -1, 0
	v_mbcnt_hi_u32_b32 v240, -1, v240
	v_readlane_b32 s100, v255, 12
	v_and_b32_e32 v241, 31, v240
	v_lshrrev_b32_e32 v242, 5, v240
	v_lshrrev_b32_e32 v243, 3, v240
	v_and_b32_e32 v244, 7, v240
	v_mov_b32_e32 v245, s100
	v_mul_u32_u24_e32 v245, 0x44, v245
	v_add_u32_e32 v245, 0x1a000, v245
	v_mul_u32_u24_e32 v252, 0x88, v241
	v_lshl_add_u32 v252, v242, 3, v252
	v_add_u32_e32 v252, v245, v252
	v_mul_u32_u24_e32 v253, 0x88, v243
	v_lshl_add_u32 v253, v244, 4, v253
	v_add_u32_e32 v253, v245, v253
	v_sub_u32_e32 v207, v243, v241
	v_lshlrev_b32_e32 v207, 12, v207
	v_lshl_add_u32 v207, v244, 4, v207
	v_lshlrev_b32_e32 v242, 3, v242
	v_sub_u32_e32 v207, v207, v242
	v_add_u32_e32 v248, v231, v207
	v_add_u32_e32 v249, 0x8000, v248
	v_add_u32_e32 v250, 0x10000, v248
	v_add_u32_e32 v251, 0x18000, v248
	ds_write_b64 v252, v[48:49]
	s_waitcnt vmcnt(26)
	v_lshlrev_b32_e32 v48, 16, v186
	v_fmac_f32_e32 v48, v230, v32
	v_and_b32_e32 v32, 0xffff0000, v186
	v_fmac_f32_e32 v32, v230, v33
	v_lshlrev_b32_e32 v33, 16, v187
	v_fmac_f32_e32 v33, v230, v34
	v_and_b32_e32 v34, 0xffff0000, v187
	v_cvt_pk_bf16_f32 v32, v48, v32
	v_fmac_f32_e32 v34, v230, v35
	v_cvt_pk_bf16_f32 v33, v33, v34
	ds_write_b64 v252, v[32:33] offset:64
	v_lshlrev_b32_e32 v32, 16, v184
	v_and_b32_e32 v33, 0xffff0000, v184
	v_fmac_f32_e32 v32, v230, v52
	v_fmac_f32_e32 v33, v230, v53
	v_cvt_pk_bf16_f32 v32, v32, v33
	v_lshlrev_b32_e32 v33, 16, v185
	v_and_b32_e32 v34, 0xffff0000, v185
	v_fmac_f32_e32 v33, v230, v54
	v_fmac_f32_e32 v34, v230, v55
	v_cvt_pk_bf16_f32 v33, v33, v34
	v_add_u32_e32 v34, 16, v231
	ds_write_b64 v252, v[32:33] offset:16
	s_waitcnt vmcnt(26)
	v_lshlrev_b32_e32 v32, 16, v180
	v_and_b32_e32 v33, 0xffff0000, v180
	v_fmac_f32_e32 v32, v230, v36
	v_fmac_f32_e32 v33, v230, v37
	v_cvt_pk_bf16_f32 v32, v32, v33
	v_lshlrev_b32_e32 v33, 16, v181
	v_and_b32_e32 v34, 0xffff0000, v181
	v_fmac_f32_e32 v33, v230, v38
	v_fmac_f32_e32 v34, v230, v39
	v_cvt_pk_bf16_f32 v33, v33, v34
	v_add_u32_e32 v34, 0x50, v231
	ds_write_b64 v252, v[32:33] offset:80
	v_lshlrev_b32_e32 v32, 16, v178
	v_and_b32_e32 v33, 0xffff0000, v178
	v_fmac_f32_e32 v32, v230, v56
	v_fmac_f32_e32 v33, v230, v57
	v_cvt_pk_bf16_f32 v32, v32, v33
	v_lshlrev_b32_e32 v33, 16, v179
	v_and_b32_e32 v34, 0xffff0000, v179
	v_fmac_f32_e32 v33, v230, v58
	v_fmac_f32_e32 v34, v230, v59
	v_cvt_pk_bf16_f32 v33, v33, v34
	v_add_u32_e32 v34, 32, v231
	ds_write_b64 v252, v[32:33] offset:32
	s_waitcnt vmcnt(26)
	v_lshlrev_b32_e32 v32, 16, v174
	v_and_b32_e32 v33, 0xffff0000, v174
	v_fmac_f32_e32 v32, v230, v40
	v_fmac_f32_e32 v33, v230, v41
	v_cvt_pk_bf16_f32 v32, v32, v33
	v_lshlrev_b32_e32 v33, 16, v175
	v_and_b32_e32 v34, 0xffff0000, v175
	v_fmac_f32_e32 v33, v230, v42
	v_fmac_f32_e32 v34, v230, v43
	v_cvt_pk_bf16_f32 v33, v33, v34
	v_add_u32_e32 v34, 0x60, v231
	ds_write_b64 v252, v[32:33] offset:96
	v_lshlrev_b32_e32 v32, 16, v172
	v_and_b32_e32 v33, 0xffff0000, v172
	v_fmac_f32_e32 v32, v230, v60
	v_fmac_f32_e32 v33, v230, v61
	v_cvt_pk_bf16_f32 v32, v32, v33
	v_lshlrev_b32_e32 v33, 16, v173
	v_and_b32_e32 v34, 0xffff0000, v173
	v_fmac_f32_e32 v33, v230, v62
	v_fmac_f32_e32 v34, v230, v63
	v_cvt_pk_bf16_f32 v33, v33, v34
	v_add_u32_e32 v34, 48, v231
	ds_write_b64 v252, v[32:33] offset:48
	s_waitcnt vmcnt(26)
	v_lshlrev_b32_e32 v32, 16, v170
	v_and_b32_e32 v33, 0xffff0000, v170
	v_fmac_f32_e32 v32, v230, v44
	v_fmac_f32_e32 v33, v230, v45
	v_cvt_pk_bf16_f32 v32, v32, v33
	v_lshlrev_b32_e32 v33, 16, v171
	v_and_b32_e32 v34, 0xffff0000, v171
	v_fmac_f32_e32 v33, v230, v46
	v_fmac_f32_e32 v34, v230, v47
	v_cvt_pk_bf16_f32 v33, v33, v34
	v_add_u32_e32 v34, 0x70, v231
	ds_write_b64 v252, v[32:33] offset:112
	s_waitcnt lgkmcnt(0)
	ds_read_b128 v[232:235], v253
	ds_read_b128 v[236:239], v253 offset:1088
	ds_read_b128 v[240:243], v253 offset:2176
	ds_read_b128 v[244:247], v253 offset:3264
	s_waitcnt lgkmcnt(0)
; #define LAS __attribute__((address_space(3)))
; DI unsigned cvt_pk_bf16(float lo, float hi) { unsigned r; asm volatile("v_cvt_pk_bf16_f32 %0, %1, %2" : "=v"(r) : "v"(lo), "v"(hi)); return r; }
; DI float bf_lo(unsigned w) { return __uint_as_float(w << 16); }
; DI float bf_hi(unsigned w) { return __uint_as_float(w & 0xffff0000u); }
; #define MFMA32(a, b, c) __builtin_amdgcn_mfma_f32_32x32x16_bf16((a), (b), (c), 0, 0, 0)
; template <bool XW, int PASS, bool RMW> ...
;     ...
;           *(u32x2*)((char*)y + (yb + 16u * gq)) = a;
;           u32x2 c2; c2.x = cvt_pk_bf16(bf_lo(ovn[4 + gq].x) + qe * yc1[4 * gq], bf_hi(ovn[4 + gq].x) + qe * yc1[4 * gq + 1]); c2.y = cvt_pk_bf16(bf_lo(ovn[4 + gq].y) + qe * yc1[4 * gq + 2], bf_hi(ovn[4 + gq].y) + qe * yc1[4 * gq + 3]);
;           *(u32x2*)((char*)y + (yb + 64u + 16u * gq)) = c2;
;         }
;         if constexpr (PASS == 1 && RMW) {
;           const unsigned ybn = yoff0 + (unsigned)cn * 524288u;
; #pragma unroll
;           for (int gq = 0; gq < 8; ++gq) ovn[gq] = *(const u32x2*)((const char*)y + (ybn + 64u * (gq >> 2) + 16u * (gq & 3)));
;         }
;       }
; #pragma unroll
;       for (int i = 0; i < 16; ++i) { st0[i] *= cd; st1[i] *= cd; }
; #pragma unroll
;       for (int sb = 0; sb < 2; ++sb) {
;         bf16x8 a0[4], a1[4];
; #pragma unroll
;         for (int k = 0; k < 4; ++k) { a0[k] = *(const LAS bf16x8*)(vimg + (cc & 1) * 16384 + (4 * sb + k) * 1024 + lane * 16); a1[k] = *(const LAS bf16x8*)(vimg + (cc & 1) * 16384 + 8192 + (4 * sb + k) * 1024 + lane * 16); }
; #pragma unroll
;         for (int k = 0; k < 4; ++k) { st0 = MFMA32(a0[k], kb0[4 * sb + k], st0); st1 = MFMA32(a1[k], kb0[4 * sb + k], st1); }
;         asm volatile("" : "+v"(st0), "+v"(st1) :: "memory");
; #pragma unroll
;         for (int k = 0; k < 4; ++k) kb0[4 * sb + k] = ldg16(kT, kboff0 + (unsigned)cn * 262144u + 1024u * (4 * sb + k));
;       }
; #pragma unroll
;       for (int t = 0; t < 2; ++t) {
;         const int sv = 2 * dq + t;
;         *(LAS bf16x8*)(vimg + ((cc + 1) & 1) * 16384 + et * 8192 + sv * 1024 + lane * 16) = scale_tab(vr[t], kdec + 16 * sv + 8 * h);
	global_store_dwordx4 v248, v[232:235], s[18:19]
	global_store_dwordx4 v249, v[236:239], s[18:19]
	global_store_dwordx4 v250, v[240:243], s[18:19]
	global_store_dwordx4 v251, v[244:247], s[18:19]
	s_nop 1
	v_lshl_add_u32 v32, v169, 19, v227
	v_or_b32_e32 v33, 16, v32
	v_add_u32_e32 v244, v32, v207
	global_load_dwordx4 v[172:175], v244, s[18:19]
	v_add_u32_e32 v245, 0x8000, v244
	global_load_dwordx4 v[184:187], v245, s[18:19]
	v_add_u32_e32 v246, 0x10000, v244
	global_load_dwordx4 v[178:181], v246, s[18:19]
	v_add_u32_e32 v247, 0x18000, v244
	global_load_dwordx4 v[208:211], v247, s[18:19]
	v_or_b32_e32 v33, 32, v32
	v_or_b32_e32 v33, 48, v32
	v_or_b32_e32 v33, 64, v32
	v_or_b32_e32 v33, 0x50, v32
	v_mov_b32_e32 v169, v168
	v_or_b32_e32 v33, 0x60, v32
	v_or_b32_e32 v32, 0x70, v32
	v_pk_mul_f32 v[30:31], v[168:169], v[30:31]
	v_pk_mul_f32 v[28:29], v[168:169], v[28:29]
	v_pk_mul_f32 v[26:27], v[168:169], v[26:27]
	v_pk_mul_f32 v[24:25], v[168:169], v[24:25]
	v_pk_mul_f32 v[22:23], v[168:169], v[22:23]
	v_pk_mul_f32 v[20:21], v[168:169], v[20:21]
	v_pk_mul_f32 v[18:19], v[168:169], v[18:19]
	v_pk_mul_f32 v[14:15], v[168:169], v[14:15]
	v_pk_mul_f32 v[12:13], v[168:169], v[12:13]
	v_pk_mul_f32 v[10:11], v[168:169], v[10:11]
	v_pk_mul_f32 v[8:9], v[168:169], v[8:9]
	v_pk_mul_f32 v[6:7], v[168:169], v[6:7]
	v_pk_mul_f32 v[4:5], v[168:169], v[4:5]
	v_pk_mul_f32 v[2:3], v[168:169], v[2:3]
	v_add_u32_e32 v169, s2, v218
	ds_read_b128 v[32:35], v169
	ds_read_b128 v[36:39], v169 offset:8192
	ds_read_b128 v[40:43], v169 offset:1024
	ds_read_b128 v[44:47], v169 offset:9216
	ds_read_b128 v[48:51], v169 offset:2048
	ds_read_b128 v[52:55], v169 offset:10240
	ds_read_b128 v[56:59], v169 offset:3072
	ds_read_b128 v[60:63], v169 offset:11264
	s_waitcnt vmcnt(33) lgkmcnt(7)
	v_mfma_f32_32x32x16_bf16 v[16:31], v[32:35], v[128:131], v[16:31]
	v_add_u32_e32 v204, v206, v223
	v_or_b32_e32 v32, 0x400, v204
	s_and_b32 s2, s1, 0x4000
	v_add_u32_e32 v231, 0xfff80000, v231
	s_cmp_eq_u32 s4, s8
	s_waitcnt lgkmcnt(6)
	v_mfma_f32_32x32x16_bf16 v[0:15], v[36:39], v[128:131], v[0:15]
	s_waitcnt vmcnt(32) lgkmcnt(5)
	v_mfma_f32_32x32x16_bf16 v[16:31], v[40:43], v[132:135], v[16:31]
	s_waitcnt lgkmcnt(4)
	v_mfma_f32_32x32x16_bf16 v[0:15], v[44:47], v[132:135], v[0:15]
	s_waitcnt vmcnt(31) lgkmcnt(3)
	v_mfma_f32_32x32x16_bf16 v[16:31], v[48:51], v[136:139], v[16:31]
	s_waitcnt lgkmcnt(2)
	v_mfma_f32_32x32x16_bf16 v[0:15], v[52:55], v[136:139], v[0:15]
	s_waitcnt vmcnt(30) lgkmcnt(1)
	v_mfma_f32_32x32x16_bf16 v[16:31], v[56:59], v[140:143], v[16:31]
	s_waitcnt lgkmcnt(0)
	v_mfma_f32_32x32x16_bf16 v[0:15], v[60:63], v[140:143], v[0:15]
	global_load_dwordx4 v[128:131], v204, s[14:15]
	global_load_dwordx4 v[132:135], v32, s[14:15]
	v_or_b32_e32 v32, 0x800, v204
	global_load_dwordx4 v[136:139], v32, s[14:15]
	v_or_b32_e32 v32, 0xc00, v204
	global_load_dwordx4 v[140:143], v32, s[14:15]
	ds_read_b128 v[32:35], v169 offset:4096
	ds_read_b128 v[36:39], v169 offset:12288
	ds_read_b128 v[40:43], v169 offset:5120
	ds_read_b128 v[44:47], v169 offset:13312
	ds_read_b128 v[48:51], v169 offset:6144
	ds_read_b128 v[52:55], v169 offset:14336
	ds_read_b128 v[56:59], v169 offset:7168
	ds_read_b128 v[60:63], v169 offset:15360
	s_waitcnt vmcnt(33) lgkmcnt(7)
	v_mfma_f32_32x32x16_bf16 v[16:31], v[32:35], v[144:147], v[16:31]
	v_or_b32_e32 v32, 0x1000, v204
	s_waitcnt lgkmcnt(6)
	v_mfma_f32_32x32x16_bf16 v[0:15], v[36:39], v[144:147], v[0:15]
	s_waitcnt vmcnt(32) lgkmcnt(5)
	v_mfma_f32_32x32x16_bf16 v[16:31], v[40:43], v[148:151], v[16:31]
	s_waitcnt vmcnt(29)
	v_lshlrev_b32_e32 v42, 16, v160
	v_add_u32_e32 v40, s2, v198
	v_lshl_add_u32 v41, v203, 19, v224
	s_mul_i32 s2, s0, 0x8400
	s_waitcnt lgkmcnt(4)
	v_mfma_f32_32x32x16_bf16 v[0:15], v[44:47], v[148:151], v[0:15]
	s_waitcnt lgkmcnt(3)
	v_mfma_f32_32x32x16_bf16 v[16:31], v[48:51], v[152:155], v[16:31]
	s_waitcnt lgkmcnt(2)
	v_mfma_f32_32x32x16_bf16 v[0:15], v[52:55], v[152:155], v[0:15]
	s_waitcnt lgkmcnt(1)
	v_mfma_f32_32x32x16_bf16 v[16:31], v[56:59], v[156:159], v[16:31]
	s_waitcnt lgkmcnt(0)
	v_mfma_f32_32x32x16_bf16 v[0:15], v[60:63], v[156:159], v[0:15]
	global_load_dwordx4 v[144:147], v32, s[14:15]
	v_or_b32_e32 v32, 0x1400, v204
	global_load_dwordx4 v[148:151], v32, s[14:15]
	v_or_b32_e32 v32, 0x1800, v204
	global_load_dwordx4 v[152:155], v32, s[14:15]
	v_or_b32_e32 v32, 0x1c00, v204
	global_load_dwordx4 v[156:159], v32, s[14:15]
	ds_read_b128 v[32:35], v228
	ds_read_b128 v[36:39], v228 offset:16
	s_waitcnt lgkmcnt(1)
	v_mul_f32_e32 v32, v32, v42
	v_and_b32_e32 v42, 0xffff0000, v160
	v_mul_f32_e32 v33, v33, v42
	v_cvt_pk_bf16_f32 v32, v32, v33
	v_lshlrev_b32_e32 v33, 16, v161
	v_mul_f32_e32 v33, v34, v33
	v_and_b32_e32 v34, 0xffff0000, v161
	v_mul_f32_e32 v34, v35, v34
	v_cvt_pk_bf16_f32 v33, v33, v34
	v_lshlrev_b32_e32 v34, 16, v162
	v_and_b32_e32 v35, 0xffff0000, v162
	s_waitcnt lgkmcnt(0)
; #define LAS __attribute__((address_space(3)))
; DI unsigned cvt_pk_bf16(float lo, float hi) { unsigned r; asm volatile("v_cvt_pk_bf16_f32 %0, %1, %2" : "=v"(r) : "v"(lo), "v"(hi)); return r; }
; template <bool XW, int PASS, bool RMW> ...
;     ...
;       for (int t = 0; t < 2; ++t) {
;         const int sv = 2 * dq + t;
;         *(LAS bf16x8*)(vimg + ((cc + 1) & 1) * 16384 + et * 8192 + sv * 1024 + lane * 16) = scale_tab(vr[t], kdec + 16 * sv + 8 * h);
;         vr[t] = ldg16(vT, vaoff0 + (unsigned)cnn * 524288u + 1024u * sv);
;       }
;       LAS bf16_t* sw = Sb + (pbuf ^ 1) * SBE + (4 * h) * 264 + 32 * w + r;
; #pragma unroll
;       for (int i = 0; i < 16; ++i) {
;         const int eo = ((i & 3) + 8 * (i >> 2)) * 264;
;         const unsigned pkw = cvt_pk_bf16(st0[i], st1[i]);
;         sw[eo] = (bf16_t)(pkw & 0xffffu);
;         sw[eo + 32 * 264] = (bf16_t)(pkw >> 16);
;       }
;       lds_barrier();
;       pbuf ^= 1;
	v_mul_f32_e32 v34, v36, v34
	v_mul_f32_e32 v35, v37, v35
	v_cvt_pk_bf16_f32 v34, v34, v35
	v_lshlrev_b32_e32 v35, 16, v163
	v_and_b32_e32 v36, 0xffff0000, v163
	v_mul_f32_e32 v35, v38, v35
	v_mul_f32_e32 v36, v39, v36
	v_cvt_pk_bf16_f32 v35, v35, v36
	v_add_u32_e32 v36, s3, v40
	ds_write_b128 v36, v[32:35]
	v_or_b32_e32 v32, s3, v41
	global_load_dwordx4 v[160:163], v32, s[16:17]
	ds_read_b128 v[32:35], v229
	ds_read_b128 v[36:39], v229 offset:16
	s_waitcnt vmcnt(33)
	v_lshlrev_b32_e32 v42, 16, v164
	s_waitcnt lgkmcnt(1)
	v_mul_f32_e32 v32, v32, v42
	v_and_b32_e32 v42, 0xffff0000, v164
	v_mul_f32_e32 v33, v33, v42
	v_cvt_pk_bf16_f32 v32, v32, v33
	v_lshlrev_b32_e32 v33, 16, v165
	v_mul_f32_e32 v33, v34, v33
	v_and_b32_e32 v34, 0xffff0000, v165
	v_mul_f32_e32 v34, v35, v34
	v_cvt_pk_bf16_f32 v33, v33, v34
	v_lshlrev_b32_e32 v34, 16, v166
	v_and_b32_e32 v35, 0xffff0000, v166
	s_waitcnt lgkmcnt(0)
	v_mul_f32_e32 v34, v36, v34
	v_mul_f32_e32 v35, v37, v35
	v_cvt_pk_bf16_f32 v34, v34, v35
	v_lshlrev_b32_e32 v35, 16, v167
	v_and_b32_e32 v36, 0xffff0000, v167
	v_mul_f32_e32 v35, v38, v35
	v_mul_f32_e32 v36, v39, v36
	v_cvt_pk_bf16_f32 v35, v35, v36
	v_add_u32_e32 v36, s33, v40
	ds_write_b128 v36, v[32:35]
	v_or_b32_e32 v32, s33, v41
	global_load_dwordx4 v[164:167], v32, s[16:17]
	v_add_u32_e32 v32, s2, v199
	v_mbcnt_lo_u32_b32 v251, -1, 0
	v_mbcnt_hi_u32_b32 v251, -1, v251
	v_and_b32_e32 v251, 1, v251
	v_sub_u32_e32 v250, 0, v251
	v_and_b32_e32 v248, 0x06060606, v250
	v_xor_b32_e32 v248, 0x05040100, v248
	v_and_b32_e32 v251, 0x107e, v250
	v_add_u32_e32 v249, v32, v251
	v_cvt_pk_bf16_f32 v232, v16, v20
	v_cvt_pk_bf16_f32 v233, v17, v21
	v_cvt_pk_bf16_f32 v234, v18, v22
	v_cvt_pk_bf16_f32 v235, v19, v23
	v_cvt_pk_bf16_f32 v236, v24, v28
	v_cvt_pk_bf16_f32 v237, v25, v29
	v_cvt_pk_bf16_f32 v238, v26, v30
	v_cvt_pk_bf16_f32 v239, v27, v31
	v_mov_b32_dpp v240, v232 quad_perm:[1,0,3,2] row_mask:0xf bank_mask:0xf
	v_mov_b32_dpp v241, v233 quad_perm:[1,0,3,2] row_mask:0xf bank_mask:0xf
	v_mov_b32_dpp v242, v234 quad_perm:[1,0,3,2] row_mask:0xf bank_mask:0xf
	v_mov_b32_dpp v243, v235 quad_perm:[1,0,3,2] row_mask:0xf bank_mask:0xf
	v_mov_b32_dpp v244, v236 quad_perm:[1,0,3,2] row_mask:0xf bank_mask:0xf
	v_mov_b32_dpp v245, v237 quad_perm:[1,0,3,2] row_mask:0xf bank_mask:0xf
	v_mov_b32_dpp v246, v238 quad_perm:[1,0,3,2] row_mask:0xf bank_mask:0xf
	v_mov_b32_dpp v247, v239 quad_perm:[1,0,3,2] row_mask:0xf bank_mask:0xf
	v_perm_b32 v240, v240, v232, v248
	v_perm_b32 v241, v241, v233, v248
	v_perm_b32 v242, v242, v234, v248
	v_perm_b32 v243, v243, v235, v248
	v_perm_b32 v244, v244, v236, v248
	v_perm_b32 v245, v245, v237, v248
	v_perm_b32 v246, v246, v238, v248
	v_perm_b32 v247, v247, v239, v248
	ds_write_b32 v249, v240 offset:0
	ds_write_b32 v249, v241 offset:528
	ds_write_b32 v249, v242 offset:1056
	ds_write_b32 v249, v243 offset:1584
	ds_write_b32 v249, v244 offset:8448
	ds_write_b32 v249, v245 offset:8976
	ds_write_b32 v249, v246 offset:9504
	ds_write_b32 v249, v247 offset:10032
	v_cvt_pk_bf16_f32 v232, v0, v4
	v_cvt_pk_bf16_f32 v233, v1, v5
	v_cvt_pk_bf16_f32 v234, v2, v6
	v_cvt_pk_bf16_f32 v235, v3, v7
	v_cvt_pk_bf16_f32 v236, v8, v12
	v_cvt_pk_bf16_f32 v237, v9, v13
	v_cvt_pk_bf16_f32 v238, v10, v14
	v_cvt_pk_bf16_f32 v239, v11, v15
	v_mov_b32_dpp v240, v232 quad_perm:[1,0,3,2] row_mask:0xf bank_mask:0xf
	v_mov_b32_dpp v241, v233 quad_perm:[1,0,3,2] row_mask:0xf bank_mask:0xf
	v_mov_b32_dpp v242, v234 quad_perm:[1,0,3,2] row_mask:0xf bank_mask:0xf
	v_mov_b32_dpp v243, v235 quad_perm:[1,0,3,2] row_mask:0xf bank_mask:0xf
	v_mov_b32_dpp v244, v236 quad_perm:[1,0,3,2] row_mask:0xf bank_mask:0xf
	v_mov_b32_dpp v245, v237 quad_perm:[1,0,3,2] row_mask:0xf bank_mask:0xf
	v_mov_b32_dpp v246, v238 quad_perm:[1,0,3,2] row_mask:0xf bank_mask:0xf
	v_mov_b32_dpp v247, v239 quad_perm:[1,0,3,2] row_mask:0xf bank_mask:0xf
	v_perm_b32 v240, v240, v232, v248
	v_perm_b32 v241, v241, v233, v248
	v_perm_b32 v242, v242, v234, v248
	v_perm_b32 v243, v243, v235, v248
	v_perm_b32 v244, v244, v236, v248
	v_perm_b32 v245, v245, v237, v248
	v_perm_b32 v246, v246, v238, v248
	v_perm_b32 v247, v247, v239, v248
	ds_write_b32 v249, v240 offset:16896
	ds_write_b32 v249, v241 offset:17424
	ds_write_b32 v249, v242 offset:17952
	ds_write_b32 v249, v243 offset:18480
	ds_write_b32 v249, v244 offset:25344
	ds_write_b32 v249, v245 offset:25872
	ds_write_b32 v249, v246 offset:26400
	ds_write_b32 v249, v247 offset:26928
	s_waitcnt lgkmcnt(0)
	s_barrier
	s_mov_b32 s2, s8
	s_mov_b32 s101, 1
	s_cbranch_scc0 .LBB0_102
